# v57: v56 + passB unit-2 stabiliser carry word requested with the gate loads in unit-1 tail (no load->vmcnt(0) on the serial waves)
# baseline (speedup 1.0000x reference)
; #define LAS __attribute__((address_space(3)))
; __device__ __forceinline__ unsigned cvt_pk_bf16(float lo, float hi) { unsigned r; asm volatile("v_cvt_pk_bf16_f32 %0, %1, %2" : "=v"(r) : "v"(lo), "v"(hi)); return r; }
; __device__ void passB_unit(const Params& p, LAS unsigned char* lds, int u, bool do_store = true) {
;     ...
;     for (int mt = 0; mt < 4; ++mt) { float sv = 0.f;
; #pragma unroll
;         for (int nt = 0; nt < 4; ++nt) { const f32x4 hv = hsum[mt][nt]; sv += (hv[0] * hv[0] + hv[1] * hv[1]) + (hv[2] * hv[2] + hv[3] * hv[3]); }
;         sv += __shfl_xor(sv, 16); sv += __shfl_xor(sv, 32);
;         if (fq == 0) ssP[w4 * 128 + wt2 * 64 + mt * 16 + fr] = sv; }
;     __syncthreads();
; #pragma unroll
;     for (int mt = 0; mt < 4; ++mt) { const int t = wt2 * 64 + mt * 16 + fr;
;         const float tot = (ssP[t] + ssP[128 + t]) + (ssP[256 + t] + ssP[384 + t]); const float rinv = rsqrtf(tot * (1.0f / 256.0f) + 1e-6f);
; #pragma unroll
;         for (int nt = 0; nt < 4; ++nt) { const int v = w4 * 64 + nt * 16 + fq * 4; const f32x4 hw = *(const f32x4*)(p.head_norm_w + h * 256 + v);
;             const f32x4 o = hsum[mt][nt] * rinv * hw;
;             u32x2 w; w.x = cvt_pk_bf16(o[0], o[1]); w.y = cvt_pk_bf16(o[2], o[3]);
;             *(LAS u32x2*)(Pd + t * 264 + v) = w; } }
.LBB0_567:
	s_or_b64 exec, exec, s[0:1]
	v_readlane_b32 s80, v254, 6
	v_readlane_b32 s82, v254, 8
	v_readlane_b32 s83, v254, 9
	s_lshl_b32 s0, s34, 10
	s_mov_b64 s[54:55], s[82:83]
	v_lshl_or_b32 v50, v223, 6, v212
	s_add_u32 s42, s54, s0
	s_addc_u32 s43, s55, 0
	v_lshlrev_b32_e32 v52, 2, v50
	s_waitcnt lgkmcnt(0)
	s_barrier
	global_load_dwordx4 v[56:59], v52, s[42:43]
	global_load_dwordx4 v[60:63], v52, s[42:43] offset:64
	global_load_dwordx4 v[64:67], v52, s[42:43] offset:128
	global_load_dwordx4 v[68:71], v52, s[42:43] offset:192
	v_lshl_add_u32 v38, v211, 2, s49
	ds_read2st64_b32 v[36:37], v38 offset1:2
	ds_read2st64_b32 v[38:39], v38 offset0:4 offset1:6
	v_mov_b32_e32 v53, 0x358637bd
	s_mov_b32 s0, 0x800000
	v_lshlrev_b32_e32 v54, 1, v50
	s_waitcnt lgkmcnt(1)
	v_mov_b32_e32 v48, v36
	s_waitcnt lgkmcnt(0)
	v_mov_b32_e32 v49, v38
	v_mov_b32_e32 v38, v37
	v_pk_add_f32 v[36:37], v[48:49], v[38:39]
	v_add3_u32 v55, s46, v210, v54
	v_add_f32_e32 v36, v36, v37
	v_fmamk_f32 v36, v36, 0x3b800000, v53
	v_mul_f32_e32 v37, 0x4b800000, v36
	v_cmp_gt_f32_e32 vcc, s0, v36
	v_readlane_b32 s81, v254, 7
	v_readlane_b32 s84, v254, 10
	v_cndmask_b32_e32 v36, v36, v37, vcc
	v_rsq_f32_e32 v36, v36
	v_readlane_b32 s85, v254, 11
	v_readlane_b32 s86, v254, 12
	v_readlane_b32 s87, v254, 13
	v_mul_f32_e32 v37, 0x45800000, v36
	v_cndmask_b32_e32 v36, v36, v37, vcc
	v_pk_mul_f32 v[38:39], v[186:187], v[36:37] op_sel_hi:[1,0]
	v_pk_mul_f32 v[48:49], v[184:185], v[36:37] op_sel_hi:[1,0]
	v_pk_mul_f32 v[50:51], v[180:181], v[36:37] op_sel_hi:[1,0]
	v_readlane_b32 s88, v254, 14
	v_readlane_b32 s89, v254, 15
	v_readlane_b32 s90, v254, 16
	v_readlane_b32 s91, v254, 17
	v_readlane_b32 s92, v254, 18
	v_readlane_b32 s93, v254, 19
	v_readlane_b32 s94, v254, 20
	v_readlane_b32 s95, v254, 21
	s_waitcnt vmcnt(0)
	v_pk_mul_f32 v[26:27], v[58:59], v[48:49]
	v_pk_mul_f32 v[24:25], v[56:57], v[38:39]
	v_pk_mul_f32 v[48:49], v[182:183], v[36:37] op_sel_hi:[1,0]
	v_cvt_pk_bf16_f32 v38, v24, v25
	v_cvt_pk_bf16_f32 v39, v26, v27
	ds_write_b64 v55, v[38:39]
	s_waitcnt vmcnt(0)
	v_pk_mul_f32 v[26:27], v[62:63], v[50:51]
	v_pk_mul_f32 v[24:25], v[60:61], v[48:49]
	v_pk_mul_f32 v[48:49], v[106:107], v[36:37] op_sel_hi:[1,0]
	v_cvt_pk_bf16_f32 v38, v24, v25
	v_cvt_pk_bf16_f32 v39, v26, v27
	v_pk_mul_f32 v[50:51], v[104:105], v[36:37] op_sel_hi:[1,0]
	ds_write_b64 v55, v[38:39] offset:32
	s_waitcnt vmcnt(0)
	v_pk_mul_f32 v[26:27], v[66:67], v[50:51]
	v_pk_mul_f32 v[24:25], v[64:65], v[48:49]
	v_pk_mul_f32 v[48:49], v[98:99], v[36:37] op_sel_hi:[1,0]
	v_cvt_pk_bf16_f32 v38, v24, v25
	v_cvt_pk_bf16_f32 v39, v26, v27
	v_pk_mul_f32 v[36:37], v[96:97], v[36:37] op_sel_hi:[1,0]
	ds_write_b64 v55, v[38:39] offset:64
	v_lshl_add_u32 v38, v213, 2, s49
	s_waitcnt vmcnt(0)
	v_pk_mul_f32 v[26:27], v[36:37], v[70:71]
	v_pk_mul_f32 v[24:25], v[48:49], v[68:69]
	s_nop 0
	v_cvt_pk_bf16_f32 v36, v24, v25
	v_cvt_pk_bf16_f32 v37, v26, v27
	ds_write_b64 v55, v[36:37] offset:96
	ds_read2st64_b32 v[36:37], v38 offset1:2
	ds_read2st64_b32 v[38:39], v38 offset0:4 offset1:6
	v_add3_u32 v55, s46, v253, v54
	s_waitcnt lgkmcnt(1)
	v_mov_b32_e32 v48, v36
	s_waitcnt lgkmcnt(0)
	v_mov_b32_e32 v49, v38
	v_mov_b32_e32 v38, v37
	v_pk_add_f32 v[36:37], v[48:49], v[38:39]
	s_nop 0
	v_add_f32_e32 v36, v36, v37
	v_fmamk_f32 v36, v36, 0x3b800000, v53
	v_mul_f32_e32 v37, 0x4b800000, v36
	v_cmp_gt_f32_e32 vcc, s0, v36
	s_nop 1
	v_cndmask_b32_e32 v36, v36, v37, vcc
	v_rsq_f32_e32 v36, v36
	s_nop 0
	v_mul_f32_e32 v37, 0x45800000, v36
	v_cndmask_b32_e32 v36, v36, v37, vcc
	v_pk_mul_f32 v[38:39], v[110:111], v[36:37] op_sel_hi:[1,0]
	v_pk_mul_f32 v[48:49], v[108:109], v[36:37] op_sel_hi:[1,0]
	v_pk_mul_f32 v[50:51], v[100:101], v[36:37] op_sel_hi:[1,0]
	v_pk_mul_f32 v[46:47], v[46:47], v[36:37] op_sel_hi:[1,0]
	v_pk_mul_f32 v[44:45], v[44:45], v[36:37] op_sel_hi:[1,0]
	v_pk_mul_f32 v[42:43], v[42:43], v[36:37] op_sel_hi:[1,0]
	s_waitcnt vmcnt(0)
	v_pk_mul_f32 v[26:27], v[58:59], v[48:49]
	v_pk_mul_f32 v[24:25], v[56:57], v[38:39]
	v_pk_mul_f32 v[48:49], v[102:103], v[36:37] op_sel_hi:[1,0]
	v_cvt_pk_bf16_f32 v38, v24, v25
	v_cvt_pk_bf16_f32 v39, v26, v27
	ds_write_b64 v55, v[38:39]
	v_pk_mul_f32 v[36:37], v[40:41], v[36:37] op_sel_hi:[1,0]
	s_waitcnt vmcnt(0)
	v_pk_mul_f32 v[26:27], v[62:63], v[50:51]
	v_pk_mul_f32 v[24:25], v[60:61], v[48:49]
	s_nop 0
	v_cvt_pk_bf16_f32 v38, v24, v25
	v_cvt_pk_bf16_f32 v39, v26, v27
	ds_write_b64 v55, v[38:39] offset:32
	s_waitcnt vmcnt(0)
	v_pk_mul_f32 v[26:27], v[66:67], v[44:45]
	v_pk_mul_f32 v[24:25], v[64:65], v[46:47]
	s_nop 0
	v_cvt_pk_bf16_f32 v38, v24, v25
	v_cvt_pk_bf16_f32 v39, v26, v27
	ds_write_b64 v55, v[38:39] offset:64
	v_lshl_add_u32 v38, v214, 2, s49
	s_waitcnt vmcnt(0)
	v_pk_mul_f32 v[26:27], v[36:37], v[70:71]
	v_pk_mul_f32 v[24:25], v[42:43], v[68:69]
	s_nop 0
	v_cvt_pk_bf16_f32 v36, v24, v25
	v_cvt_pk_bf16_f32 v37, v26, v27
	ds_write_b64 v55, v[36:37] offset:96
	ds_read2st64_b32 v[36:37], v38 offset1:2
	ds_read2st64_b32 v[38:39], v38 offset0:4 offset1:6
	s_waitcnt lgkmcnt(1)
	v_mov_b32_e32 v40, v36
	s_waitcnt lgkmcnt(0)
; #define LAS __attribute__((address_space(3)))
; __device__ __forceinline__ unsigned cvt_pk_bf16(float lo, float hi) { unsigned r; asm volatile("v_cvt_pk_bf16_f32 %0, %1, %2" : "=v"(r) : "v"(lo), "v"(hi)); return r; }
; __device__ void passB_unit(const Params& p, LAS unsigned char* lds, int u, bool do_store = true) {
;     ...
;     if (tid < 256) { const int d = tid >> 7, t = sc_t; if (wid & 1) sc_pm = fmaxf(sc_pm, wmax[wid - 1]);
;         const float mc = ((const float*)(p.ws + OFF_MST))[(sid0 + d) * 16 + c];
;     ...
; #pragma unroll
;     for (int mt = 0; mt < 4; ++mt) { const int t = wt2 * 64 + mt * 16 + fr;
;         const float tot = (ssP[t] + ssP[128 + t]) + (ssP[256 + t] + ssP[384 + t]); const float rinv = rsqrtf(tot * (1.0f / 256.0f) + 1e-6f);
; #pragma unroll
;         for (int nt = 0; nt < 4; ++nt) { const int v = w4 * 64 + nt * 16 + fq * 4; const f32x4 hw = *(const f32x4*)(p.head_norm_w + h * 256 + v);
;             const f32x4 o = hsum[mt][nt] * rinv * hw;
;             u32x2 w; w.x = cvt_pk_bf16(o[0], o[1]); w.y = cvt_pk_bf16(o[2], o[3]);
;             *(LAS u32x2*)(Pd + t * 264 + v) = w; } }
	v_mov_b32_e32 v41, v38
	v_mov_b32_e32 v38, v37
	v_pk_add_f32 v[36:37], v[40:41], v[38:39]
	s_nop 0
	v_add_f32_e32 v36, v36, v37
	v_fmamk_f32 v36, v36, 0x3b800000, v53
	v_mul_f32_e32 v37, 0x4b800000, v36
	v_cmp_gt_f32_e32 vcc, s0, v36
	s_nop 1
	v_cndmask_b32_e32 v36, v36, v37, vcc
	v_rsq_f32_e32 v36, v36
	s_nop 0
	v_mul_f32_e32 v37, 0x45800000, v36
	v_cndmask_b32_e32 v36, v36, v37, vcc
	v_pk_mul_f32 v[32:33], v[32:33], v[36:37] op_sel_hi:[1,0]
	v_pk_mul_f32 v[34:35], v[34:35], v[36:37] op_sel_hi:[1,0]
	v_pk_mul_f32 v[22:23], v[22:23], v[36:37] op_sel_hi:[1,0]
	v_pk_mul_f32 v[20:21], v[20:21], v[36:37] op_sel_hi:[1,0]
	v_pk_mul_f32 v[18:19], v[18:19], v[36:37] op_sel_hi:[1,0]
	v_pk_mul_f32 v[14:15], v[14:15], v[36:37] op_sel_hi:[1,0]
	v_pk_mul_f32 v[10:11], v[10:11], v[36:37] op_sel_hi:[1,0]
	v_pk_mul_f32 v[8:9], v[8:9], v[36:37] op_sel_hi:[1,0]
	s_waitcnt vmcnt(0)
	v_pk_mul_f32 v[26:27], v[58:59], v[34:35]
	v_pk_mul_f32 v[24:25], v[56:57], v[32:33]
	v_add3_u32 v34, s46, v252, v54
	v_cvt_pk_bf16_f32 v32, v24, v25
	v_cvt_pk_bf16_f32 v33, v26, v27
	ds_write_b64 v34, v[32:33]
	s_waitcnt vmcnt(0)
	v_pk_mul_f32 v[20:21], v[62:63], v[20:21]
	v_pk_mul_f32 v[22:23], v[60:61], v[22:23]
	s_nop 0
	v_cvt_pk_bf16_f32 v24, v22, v23
	v_cvt_pk_bf16_f32 v25, v20, v21
	ds_write_b64 v34, v[24:25] offset:32
	s_waitcnt vmcnt(0)
	v_pk_mul_f32 v[18:19], v[64:65], v[18:19]
	v_pk_mul_f32 v[14:15], v[66:67], v[14:15]
	v_cvt_pk_bf16_f32 v22, v18, v19
	s_nop 0
	v_cvt_pk_bf16_f32 v23, v14, v15
	ds_write_b64 v34, v[22:23] offset:64
	s_waitcnt vmcnt(0)
	v_pk_mul_f32 v[8:9], v[8:9], v[70:71]
	v_pk_mul_f32 v[10:11], v[10:11], v[68:69]
	v_lshl_add_u32 v18, v215, 2, s49
	v_cvt_pk_bf16_f32 v14, v10, v11
	v_cvt_pk_bf16_f32 v15, v8, v9
	ds_write_b64 v34, v[14:15] offset:96
	ds_read2st64_b32 v[14:15], v18 offset1:2
	ds_read2st64_b32 v[18:19], v18 offset0:4 offset1:6
	s_waitcnt lgkmcnt(1)
	v_mov_b32_e32 v20, v14
	s_waitcnt lgkmcnt(0)
	v_mov_b32_e32 v21, v18
	v_mov_b32_e32 v18, v15
	v_pk_add_f32 v[14:15], v[20:21], v[18:19]
	s_nop 0
	v_add_f32_e32 v14, v14, v15
	v_fmac_f32_e32 v53, 0x3b800000, v14
	v_mul_f32_e32 v14, 0x4b800000, v53
	v_cmp_gt_f32_e32 vcc, s0, v53
	s_mov_b32 s0, 0
	s_nop 0
	v_cndmask_b32_e32 v14, v53, v14, vcc
	v_rsq_f32_e32 v14, v14
	s_nop 0
	v_mul_f32_e32 v15, 0x45800000, v14
	v_cndmask_b32_e32 v14, v14, v15, vcc
	v_pk_mul_f32 v[18:19], v[28:29], v[14:15] op_sel_hi:[1,0]
	v_pk_mul_f32 v[20:21], v[30:31], v[14:15] op_sel_hi:[1,0]
	v_add3_u32 v15, s46, v227, v54
	v_pk_mul_f32 v[16:17], v[16:17], v[14:15] op_sel_hi:[1,0]
	v_pk_mul_f32 v[6:7], v[6:7], v[14:15] op_sel_hi:[1,0]
	v_pk_mul_f32 v[12:13], v[12:13], v[14:15] op_sel_hi:[1,0]
	v_pk_mul_f32 v[4:5], v[4:5], v[14:15] op_sel_hi:[1,0]
	v_pk_mul_f32 v[2:3], v[2:3], v[14:15] op_sel_hi:[1,0]
	v_pk_mul_f32 v[0:1], v[0:1], v[14:15] op_sel_hi:[1,0]
	s_waitcnt vmcnt(0)
	v_pk_mul_f32 v[10:11], v[58:59], v[20:21]
	v_pk_mul_f32 v[8:9], v[56:57], v[18:19]
	s_nop 0
	v_cvt_pk_bf16_f32 v18, v8, v9
	v_cvt_pk_bf16_f32 v19, v10, v11
	ds_write_b64 v15, v[18:19]
	s_waitcnt vmcnt(0)
	v_pk_mul_f32 v[6:7], v[62:63], v[6:7]
	v_pk_mul_f32 v[8:9], v[60:61], v[16:17]
	s_nop 0
	v_cvt_pk_bf16_f32 v10, v8, v9
	v_cvt_pk_bf16_f32 v11, v6, v7
	ds_write_b64 v15, v[10:11] offset:32
	s_waitcnt vmcnt(0)
	v_pk_mul_f32 v[4:5], v[66:67], v[4:5]
	v_pk_mul_f32 v[6:7], v[64:65], v[12:13]
	s_nop 0
	v_cvt_pk_bf16_f32 v8, v6, v7
	v_cvt_pk_bf16_f32 v9, v4, v5
	ds_write_b64 v15, v[8:9] offset:64
	s_waitcnt vmcnt(0)
	v_pk_mul_f32 v[0:1], v[0:1], v[70:71]
	v_pk_mul_f32 v[2:3], v[2:3], v[68:69]
	s_nop 0
	v_cvt_pk_bf16_f32 v2, v2, v3
	v_cvt_pk_bf16_f32 v3, v0, v1
	ds_write_b64 v15, v[2:3] offset:96
	s_waitcnt lgkmcnt(0)
	s_barrier
	v_cmp_gt_u32_e32 vcc, 0x100, v224
	s_and_saveexec_b64 s[62:63], vcc
	s_ashr_i32 s65, s40, 31
	s_mov_b32 s64, s40
	s_lshl_b64 s[64:65], s[64:65], 17
	s_add_u32 s64, s70, s64
	s_addc_u32 s65, s71, s65
	s_or_b32 s66, s52, 1
	s_lshl_b32 s66, s66, 9
	s_add_u32 s64, s64, s66
	s_addc_u32 s65, s65, 0
	s_add_u32 s64, s64, 0xfc00000
	s_addc_u32 s65, s65, 0
	s_movk_i32 s67, 0x7f
	v_and_b32_e32 v74, 0x7f, v224
	v_bitop3_b32 v75, v224, s67, v224 bitop3:0xc
	v_cmp_gt_u32_e32 vcc, 0x80, v224
	s_nop 1
	v_cndmask_b32_e32 v74, v75, v74, vcc
	v_ashrrev_i32_e32 v75, 4, v224
	v_and_or_b32 v75, v75, -8, s34
	v_or_b32_e32 v76, 4, v75
	v_ashrrev_i32_e32 v77, 31, v76
	v_lshlrev_b64 v[76:77], 13, v[76:77]
	v_lshlrev_b32_e32 v78, 2, v74
	v_mov_b32_e32 v79, 0
	v_lshl_add_u64 v[76:77], s[64:65], 0, v[76:77]
	v_lshl_add_u64 v[76:77], v[76:77], 0, v[78:79]
	global_load_dword v72, v[76:77], off
	v_mov_b32_e32 v80, v75
	v_ashrrev_i32_e32 v81, 31, v75
	v_lshlrev_b64 v[80:81], 13, v[80:81]
	v_lshl_add_u64 v[80:81], s[64:65], 0, v[80:81]
	v_lshl_add_u64 v[80:81], v[80:81], 0, v[78:79]
	global_load_dword v73, v[80:81], off
	s_or_b32 s66, s52, 1
	v_ashrrev_i32_e32 v83, 7, v224
	v_add_u32_e32 v83, s50, v83
	v_lshl_or_b32 v84, v83, 4, s66
	v_ashrrev_i32_e32 v85, 31, v84
	v_lshl_add_u64 v[84:85], v[84:85], 2, s[14:15]
	global_load_dword v82, v[84:85], off
	s_or_b64 exec, exec, s[62:63]
	v_or_b32_e32 v2, v198, v199
	v_add_u32_e32 v0, s46, v203
	v_or_b32_e32 v1, v202, v201
	s_mov_b32 s1, 0xfffffc0
	s_movk_i32 s4, 0x210
	v_lshlrev_b32_e32 v2, 6, v2

; #define LAS __attribute__((address_space(3)))
; __device__ __forceinline__ float bf_lo(unsigned w) { return __uint_as_float(w << 16); }
; __device__ __forceinline__ float bf_hi(unsigned w) { return __uint_as_float(w & 0xffff0000u); }
; __device__ void passB_unit(const Params& p, LAS unsigned char* lds, int u, bool do_store = true) {
;     ...
;     if (tid < 256) { const int d = tid >> 7, t = sc_t; if (wid & 1) sc_pm = fmaxf(sc_pm, wmax[wid - 1]);
;         const float mc = ((const float*)(p.ws + OFF_MST))[(sid0 + d) * 16 + c];
;         const float Mt = fmaxf(mc, sc_pm); const int dt = d * 128 + t;
;         aA[dt] = sc_a; MA[dt] = Mt; winA[dt] = expf(mc - Mt); clampA[dt] = expf(-(sc_b + Mt));
;         float s = 0.f; const LAS float* nv = nvec + d * 256;
; #pragma unroll 4
;         for (int k8 = 0; k8 < 32; ++k8) { const u32x4 qv = *(const LAS u32x4*)(Qs + t * 264 + k8 * 8); const LAS float* np = nv + k8 * 8;
;             s += bf_lo(qv.x) * np[0] + bf_hi(qv.x) * np[1] + bf_lo(qv.y) * np[2] + bf_hi(qv.y) * np[3] + bf_lo(qv.z) * np[4] + bf_hi(qv.z) * np[5] + bf_lo(qv.w) * np[6] + bf_hi(qv.w) * np[7]; }
;         nqA[dt] = s; }
.LBB0_582:
	s_or_b64 exec, exec, s[6:7]
	v_ashrrev_i32_e32 v71, 7, v196
	v_add_u32_e32 v60, s50, v71
	v_lshl_or_b32 v72, v60, 4, s24
	v_ashrrev_i32_e32 v73, 31, v72
	v_lshl_add_u64 v[72:73], v[72:73], 2, s[14:15]
	v_mov_b32_e32 v72, v82
	v_max_f32_e32 v70, v70, v70
	s_mov_b32 s10, 0x3fb8aa3b
	s_mov_b32 s15, 0xbfb8aa3b
	s_movk_i32 s7, 0xff80
	s_movk_i32 s28, 0x210
	v_and_or_b32 v74, v196, s7, v63
	v_mad_i32_i24 v68, v63, s28, 0
	v_lshl_add_u32 v63, v74, 2, 0
	s_mov_b32 s11, 0xc2ce8ed0
	v_add_u32_e32 v74, 0x22000, v63
	s_mov_b32 s25, 0x42ce8ed0
	v_add_u32_e32 v75, 0x22400, v63
	s_mov_b32 s14, 0x42b17218
	v_mov_b32_e32 v73, 0x7f800000
	s_mov_b32 s26, 0xc2b17218
	v_add_u32_e32 v76, 0x22800, v63
	s_mov_b32 s6, 0
	v_mov_b32_e32 v60, 0
	v_add_u32_e32 v77, 0x22c00, v63
	s_waitcnt vmcnt(0)
	v_max_f32_e32 v78, v72, v72
	v_max_f32_e32 v70, v78, v70
	v_sub_f32_e32 v72, v72, v70
	v_add_f32_e32 v69, v69, v70
	v_mul_f32_e32 v78, 0x3fb8aa3b, v72
	v_mul_f32_e32 v79, 0xbfb8aa3b, v69
	v_fma_f32 v80, v72, s10, -v78
	v_rndne_f32_e32 v81, v78
	v_fma_f32 v82, v69, s15, -v79
	v_rndne_f32_e32 v83, v79
	v_fmamk_f32 v80, v72, 0x32a5705f, v80
	v_sub_f32_e32 v78, v78, v81
	v_fmamk_f32 v82, v69, 0xb2a5705f, v82
	v_sub_f32_e32 v79, v79, v83
	v_add_f32_e32 v78, v78, v80
	v_cvt_i32_f32_e32 v81, v81
	v_add_f32_e32 v79, v79, v82
	v_exp_f32_e32 v78, v78
	v_cvt_i32_f32_e32 v83, v83
	v_exp_f32_e32 v79, v79
	ds_write_b32 v74, v61
	ds_write_b32 v75, v70
	v_ldexp_f32 v61, v78, v81
	v_cmp_ngt_f32_e32 vcc, s11, v72
	v_ldexp_f32 v70, v79, v83
	s_nop 0
	v_cndmask_b32_e32 v61, 0, v61, vcc
	v_cmp_nlt_f32_e32 vcc, s25, v69
	s_nop 1
	v_cndmask_b32_e32 v70, 0, v70, vcc
	v_cmp_nlt_f32_e32 vcc, s14, v72
	s_nop 1
	v_cndmask_b32_e32 v61, v73, v61, vcc
	v_cmp_ngt_f32_e32 vcc, s26, v69
	s_nop 1
	v_cndmask_b32_e32 v69, v73, v70, vcc
	ds_write_b32 v76, v61
	ds_write_b32 v77, v69
	v_lshl_add_u32 v61, v71, 10, 0
	v_add_u32_e32 v69, 0x23400, v61
	s_mov_b32 s7, 0xffff0000
	ds_read_b128 v[70:73], v68 offset:0
	ds_read_b128 v[94:97], v69 offset:0
	ds_read_b128 v[98:101], v69 offset:16
	ds_read_b128 v[74:77], v68 offset:16
	ds_read_b128 v[102:105], v69 offset:32
	ds_read_b128 v[106:109], v69 offset:48
	ds_read_b128 v[78:81], v68 offset:32
	ds_read_b128 v[110:113], v69 offset:64
	ds_read_b128 v[114:117], v69 offset:80
	ds_read_b128 v[82:85], v68 offset:48
	ds_read_b128 v[118:121], v69 offset:96
	ds_read_b128 v[122:125], v69 offset:112
	ds_read_b128 v[142:145], v68 offset:64
	ds_read_b128 v[160:163], v69 offset:128
	ds_read_b128 v[164:167], v69 offset:144
	ds_read_b128 v[146:149], v68 offset:80
	ds_read_b128 v[168:171], v69 offset:160
	ds_read_b128 v[172:175], v69 offset:176
	ds_read_b128 v[150:153], v68 offset:96
	ds_read_b128 v[176:179], v69 offset:192
	ds_read_b128 v[180:183], v69 offset:208
	ds_read_b128 v[154:157], v68 offset:112
	ds_read_b128 v[184:187], v69 offset:224
	ds_read_b128 v[188:191], v69 offset:240
	s_waitcnt lgkmcnt(15)
	v_lshlrev_b32_e32 v126, 16, v70
	v_and_b32_e32 v127, s7, v70
	v_pk_mul_f32 v[86:87], v[94:95], v[126:127]
	v_lshlrev_b32_e32 v128, 16, v71
	v_and_b32_e32 v129, s7, v71
	v_pk_mul_f32 v[192:193], v[96:97], v[128:129]
	v_lshlrev_b32_e32 v130, 16, v72
	v_and_b32_e32 v131, s7, v72
	v_pk_mul_f32 v[194:195], v[98:99], v[130:131]
	v_lshlrev_b32_e32 v132, 16, v73
	v_and_b32_e32 v133, s7, v73
	v_pk_mul_f32 v[204:205], v[100:101], v[132:133]
	s_waitcnt lgkmcnt(15)
	v_lshlrev_b32_e32 v134, 16, v74
	v_and_b32_e32 v135, s7, v74
	v_pk_fma_f32 v[86:87], v[102:103], v[134:135], v[86:87]
	v_lshlrev_b32_e32 v136, 16, v75
	v_and_b32_e32 v137, s7, v75
	v_pk_fma_f32 v[192:193], v[104:105], v[136:137], v[192:193]
	v_lshlrev_b32_e32 v138, 16, v76
	v_and_b32_e32 v139, s7, v76
	v_pk_fma_f32 v[194:195], v[106:107], v[138:139], v[194:195]
	v_lshlrev_b32_e32 v140, 16, v77
	v_and_b32_e32 v141, s7, v77
	v_pk_fma_f32 v[204:205], v[108:109], v[140:141], v[204:205]
	s_waitcnt lgkmcnt(15)
	v_lshlrev_b32_e32 v126, 16, v78
	v_and_b32_e32 v127, s7, v78
	v_pk_fma_f32 v[86:87], v[110:111], v[126:127], v[86:87]
	v_lshlrev_b32_e32 v128, 16, v79
	v_and_b32_e32 v129, s7, v79
	v_pk_fma_f32 v[192:193], v[112:113], v[128:129], v[192:193]
	v_lshlrev_b32_e32 v130, 16, v80
	v_and_b32_e32 v131, s7, v80
	v_pk_fma_f32 v[194:195], v[114:115], v[130:131], v[194:195]
	v_lshlrev_b32_e32 v132, 16, v81
	v_and_b32_e32 v133, s7, v81
	v_pk_fma_f32 v[204:205], v[116:117], v[132:133], v[204:205]
	s_waitcnt lgkmcnt(12)
	v_lshlrev_b32_e32 v134, 16, v82
	v_and_b32_e32 v135, s7, v82
	v_pk_fma_f32 v[86:87], v[118:119], v[134:135], v[86:87]
	v_lshlrev_b32_e32 v136, 16, v83
	v_and_b32_e32 v137, s7, v83
	v_pk_fma_f32 v[192:193], v[120:121], v[136:137], v[192:193]
	v_lshlrev_b32_e32 v138, 16, v84
	v_and_b32_e32 v139, s7, v84
	v_pk_fma_f32 v[194:195], v[122:123], v[138:139], v[194:195]
	v_lshlrev_b32_e32 v140, 16, v85
	v_and_b32_e32 v141, s7, v85
	v_pk_fma_f32 v[204:205], v[124:125], v[140:141], v[204:205]
	ds_read_b128 v[70:73], v68 offset:128
	ds_read_b128 v[94:97], v69 offset:256
	ds_read_b128 v[98:101], v69 offset:272
	ds_read_b128 v[74:77], v68 offset:144
	ds_read_b128 v[102:105], v69 offset:288
	ds_read_b128 v[106:109], v69 offset:304
	ds_read_b128 v[78:81], v68 offset:160
	ds_read_b128 v[110:113], v69 offset:320
	ds_read_b128 v[114:117], v69 offset:336
	ds_read_b128 v[82:85], v68 offset:176
	ds_read_b128 v[118:121], v69 offset:352
	ds_read_b128 v[122:125], v69 offset:368
	s_waitcnt lgkmcnt(15)
; #define LAS __attribute__((address_space(3)))
; __device__ __forceinline__ float bf_lo(unsigned w) { return __uint_as_float(w << 16); }
; __device__ __forceinline__ float bf_hi(unsigned w) { return __uint_as_float(w & 0xffff0000u); }
; __device__ void passB_unit(const Params& p, LAS unsigned char* lds, int u, bool do_store = true) {
;     ...
;         for (int k8 = 0; k8 < 32; ++k8) { const u32x4 qv = *(const LAS u32x4*)(Qs + t * 264 + k8 * 8); const LAS float* np = nv + k8 * 8;
;             s += bf_lo(qv.x) * np[0] + bf_hi(qv.x) * np[1] + bf_lo(qv.y) * np[2] + bf_hi(qv.y) * np[3] + bf_lo(qv.z) * np[4] + bf_hi(qv.z) * np[5] + bf_lo(qv.w) * np[6] + bf_hi(qv.w) * np[7]; }
	v_lshlrev_b32_e32 v126, 16, v142
	v_and_b32_e32 v127, s7, v142
	v_pk_fma_f32 v[86:87], v[160:161], v[126:127], v[86:87]
	v_lshlrev_b32_e32 v128, 16, v143
	v_and_b32_e32 v129, s7, v143
	v_pk_fma_f32 v[192:193], v[162:163], v[128:129], v[192:193]
	v_lshlrev_b32_e32 v130, 16, v144
	v_and_b32_e32 v131, s7, v144
	v_pk_fma_f32 v[194:195], v[164:165], v[130:131], v[194:195]
	v_lshlrev_b32_e32 v132, 16, v145
	v_and_b32_e32 v133, s7, v145
	v_pk_fma_f32 v[204:205], v[166:167], v[132:133], v[204:205]
	s_waitcnt lgkmcnt(15)
	v_lshlrev_b32_e32 v134, 16, v146
	v_and_b32_e32 v135, s7, v146
	v_pk_fma_f32 v[86:87], v[168:169], v[134:135], v[86:87]
	v_lshlrev_b32_e32 v136, 16, v147
	v_and_b32_e32 v137, s7, v147
	v_pk_fma_f32 v[192:193], v[170:171], v[136:137], v[192:193]
	v_lshlrev_b32_e32 v138, 16, v148
	v_and_b32_e32 v139, s7, v148
	v_pk_fma_f32 v[194:195], v[172:173], v[138:139], v[194:195]
	v_lshlrev_b32_e32 v140, 16, v149
	v_and_b32_e32 v141, s7, v149
	v_pk_fma_f32 v[204:205], v[174:175], v[140:141], v[204:205]
	s_waitcnt lgkmcnt(15)
	v_lshlrev_b32_e32 v126, 16, v150
	v_and_b32_e32 v127, s7, v150
	v_pk_fma_f32 v[86:87], v[176:177], v[126:127], v[86:87]
	v_lshlrev_b32_e32 v128, 16, v151
	v_and_b32_e32 v129, s7, v151
	v_pk_fma_f32 v[192:193], v[178:179], v[128:129], v[192:193]
	v_lshlrev_b32_e32 v130, 16, v152
	v_and_b32_e32 v131, s7, v152
	v_pk_fma_f32 v[194:195], v[180:181], v[130:131], v[194:195]
	v_lshlrev_b32_e32 v132, 16, v153
	v_and_b32_e32 v133, s7, v153
	v_pk_fma_f32 v[204:205], v[182:183], v[132:133], v[204:205]
	s_waitcnt lgkmcnt(12)
	v_lshlrev_b32_e32 v134, 16, v154
	v_and_b32_e32 v135, s7, v154
	v_pk_fma_f32 v[86:87], v[184:185], v[134:135], v[86:87]
	v_lshlrev_b32_e32 v136, 16, v155
	v_and_b32_e32 v137, s7, v155
	v_pk_fma_f32 v[192:193], v[186:187], v[136:137], v[192:193]
	v_lshlrev_b32_e32 v138, 16, v156
	v_and_b32_e32 v139, s7, v156
	v_pk_fma_f32 v[194:195], v[188:189], v[138:139], v[194:195]
	v_lshlrev_b32_e32 v140, 16, v157
	v_and_b32_e32 v141, s7, v157
	v_pk_fma_f32 v[204:205], v[190:191], v[140:141], v[204:205]
	ds_read_b128 v[142:145], v68 offset:192
	ds_read_b128 v[160:163], v69 offset:384
	ds_read_b128 v[164:167], v69 offset:400
	ds_read_b128 v[146:149], v68 offset:208
	ds_read_b128 v[168:171], v69 offset:416
	ds_read_b128 v[172:175], v69 offset:432
	ds_read_b128 v[150:153], v68 offset:224
	ds_read_b128 v[176:179], v69 offset:448
	ds_read_b128 v[180:183], v69 offset:464
	ds_read_b128 v[154:157], v68 offset:240
	ds_read_b128 v[184:187], v69 offset:480
	ds_read_b128 v[188:191], v69 offset:496
	s_waitcnt lgkmcnt(15)
	v_lshlrev_b32_e32 v126, 16, v70
	v_and_b32_e32 v127, s7, v70
	v_pk_fma_f32 v[86:87], v[94:95], v[126:127], v[86:87]
	v_lshlrev_b32_e32 v128, 16, v71
	v_and_b32_e32 v129, s7, v71
	v_pk_fma_f32 v[192:193], v[96:97], v[128:129], v[192:193]
	v_lshlrev_b32_e32 v130, 16, v72
	v_and_b32_e32 v131, s7, v72
	v_pk_fma_f32 v[194:195], v[98:99], v[130:131], v[194:195]
	v_lshlrev_b32_e32 v132, 16, v73
	v_and_b32_e32 v133, s7, v73
	v_pk_fma_f32 v[204:205], v[100:101], v[132:133], v[204:205]
	s_waitcnt lgkmcnt(15)
	v_lshlrev_b32_e32 v134, 16, v74
	v_and_b32_e32 v135, s7, v74
	v_pk_fma_f32 v[86:87], v[102:103], v[134:135], v[86:87]
	v_lshlrev_b32_e32 v136, 16, v75
	v_and_b32_e32 v137, s7, v75
	v_pk_fma_f32 v[192:193], v[104:105], v[136:137], v[192:193]
	v_lshlrev_b32_e32 v138, 16, v76
	v_and_b32_e32 v139, s7, v76
	v_pk_fma_f32 v[194:195], v[106:107], v[138:139], v[194:195]
	v_lshlrev_b32_e32 v140, 16, v77
	v_and_b32_e32 v141, s7, v77
	v_pk_fma_f32 v[204:205], v[108:109], v[140:141], v[204:205]
	s_waitcnt lgkmcnt(15)
	v_lshlrev_b32_e32 v126, 16, v78
	v_and_b32_e32 v127, s7, v78
	v_pk_fma_f32 v[86:87], v[110:111], v[126:127], v[86:87]
	v_lshlrev_b32_e32 v128, 16, v79
	v_and_b32_e32 v129, s7, v79
	v_pk_fma_f32 v[192:193], v[112:113], v[128:129], v[192:193]
	v_lshlrev_b32_e32 v130, 16, v80
	v_and_b32_e32 v131, s7, v80
	v_pk_fma_f32 v[194:195], v[114:115], v[130:131], v[194:195]
	v_lshlrev_b32_e32 v132, 16, v81
	v_and_b32_e32 v133, s7, v81
	v_pk_fma_f32 v[204:205], v[116:117], v[132:133], v[204:205]
	s_waitcnt lgkmcnt(12)
	v_lshlrev_b32_e32 v134, 16, v82
	v_and_b32_e32 v135, s7, v82
	v_pk_fma_f32 v[86:87], v[118:119], v[134:135], v[86:87]
	v_lshlrev_b32_e32 v136, 16, v83
	v_and_b32_e32 v137, s7, v83
	v_pk_fma_f32 v[192:193], v[120:121], v[136:137], v[192:193]
	v_lshlrev_b32_e32 v138, 16, v84
	v_and_b32_e32 v139, s7, v84
	v_pk_fma_f32 v[194:195], v[122:123], v[138:139], v[194:195]
	v_lshlrev_b32_e32 v140, 16, v85
	v_and_b32_e32 v141, s7, v85
	v_pk_fma_f32 v[204:205], v[124:125], v[140:141], v[204:205]
	ds_read_b128 v[70:73], v68 offset:256
	ds_read_b128 v[94:97], v69 offset:512
	ds_read_b128 v[98:101], v69 offset:528
	ds_read_b128 v[74:77], v68 offset:272
	ds_read_b128 v[102:105], v69 offset:544
	ds_read_b128 v[106:109], v69 offset:560
	ds_read_b128 v[78:81], v68 offset:288
	ds_read_b128 v[110:113], v69 offset:576
	ds_read_b128 v[114:117], v69 offset:592
	ds_read_b128 v[82:85], v68 offset:304
	ds_read_b128 v[118:121], v69 offset:608
	ds_read_b128 v[122:125], v69 offset:624
	s_waitcnt lgkmcnt(15)
	v_lshlrev_b32_e32 v126, 16, v142
	v_and_b32_e32 v127, s7, v142
	v_pk_fma_f32 v[86:87], v[160:161], v[126:127], v[86:87]
	v_lshlrev_b32_e32 v128, 16, v143
	v_and_b32_e32 v129, s7, v143
	v_pk_fma_f32 v[192:193], v[162:163], v[128:129], v[192:193]
	v_lshlrev_b32_e32 v130, 16, v144
	v_and_b32_e32 v131, s7, v144
	v_pk_fma_f32 v[194:195], v[164:165], v[130:131], v[194:195]
	v_lshlrev_b32_e32 v132, 16, v145
	v_and_b32_e32 v133, s7, v145
	v_pk_fma_f32 v[204:205], v[166:167], v[132:133], v[204:205]
	s_waitcnt lgkmcnt(15)
; #define LAS __attribute__((address_space(3)))
; __device__ __forceinline__ float bf_lo(unsigned w) { return __uint_as_float(w << 16); }
; __device__ __forceinline__ float bf_hi(unsigned w) { return __uint_as_float(w & 0xffff0000u); }
; __device__ void passB_unit(const Params& p, LAS unsigned char* lds, int u, bool do_store = true) {
;     ...
;         for (int k8 = 0; k8 < 32; ++k8) { const u32x4 qv = *(const LAS u32x4*)(Qs + t * 264 + k8 * 8); const LAS float* np = nv + k8 * 8;
;             s += bf_lo(qv.x) * np[0] + bf_hi(qv.x) * np[1] + bf_lo(qv.y) * np[2] + bf_hi(qv.y) * np[3] + bf_lo(qv.z) * np[4] + bf_hi(qv.z) * np[5] + bf_lo(qv.w) * np[6] + bf_hi(qv.w) * np[7]; }
	v_lshlrev_b32_e32 v134, 16, v146
	v_and_b32_e32 v135, s7, v146
	v_pk_fma_f32 v[86:87], v[168:169], v[134:135], v[86:87]
	v_lshlrev_b32_e32 v136, 16, v147
	v_and_b32_e32 v137, s7, v147
	v_pk_fma_f32 v[192:193], v[170:171], v[136:137], v[192:193]
	v_lshlrev_b32_e32 v138, 16, v148
	v_and_b32_e32 v139, s7, v148
	v_pk_fma_f32 v[194:195], v[172:173], v[138:139], v[194:195]
	v_lshlrev_b32_e32 v140, 16, v149
	v_and_b32_e32 v141, s7, v149
	v_pk_fma_f32 v[204:205], v[174:175], v[140:141], v[204:205]
	s_waitcnt lgkmcnt(15)
	v_lshlrev_b32_e32 v126, 16, v150
	v_and_b32_e32 v127, s7, v150
	v_pk_fma_f32 v[86:87], v[176:177], v[126:127], v[86:87]
	v_lshlrev_b32_e32 v128, 16, v151
	v_and_b32_e32 v129, s7, v151
	v_pk_fma_f32 v[192:193], v[178:179], v[128:129], v[192:193]
	v_lshlrev_b32_e32 v130, 16, v152
	v_and_b32_e32 v131, s7, v152
	v_pk_fma_f32 v[194:195], v[180:181], v[130:131], v[194:195]
	v_lshlrev_b32_e32 v132, 16, v153
	v_and_b32_e32 v133, s7, v153
	v_pk_fma_f32 v[204:205], v[182:183], v[132:133], v[204:205]
	s_waitcnt lgkmcnt(12)
	v_lshlrev_b32_e32 v134, 16, v154
	v_and_b32_e32 v135, s7, v154
	v_pk_fma_f32 v[86:87], v[184:185], v[134:135], v[86:87]
	v_lshlrev_b32_e32 v136, 16, v155
	v_and_b32_e32 v137, s7, v155
	v_pk_fma_f32 v[192:193], v[186:187], v[136:137], v[192:193]
	v_lshlrev_b32_e32 v138, 16, v156
	v_and_b32_e32 v139, s7, v156
	v_pk_fma_f32 v[194:195], v[188:189], v[138:139], v[194:195]
	v_lshlrev_b32_e32 v140, 16, v157
	v_and_b32_e32 v141, s7, v157
	v_pk_fma_f32 v[204:205], v[190:191], v[140:141], v[204:205]
	ds_read_b128 v[142:145], v68 offset:320
	ds_read_b128 v[160:163], v69 offset:640
	ds_read_b128 v[164:167], v69 offset:656
	ds_read_b128 v[146:149], v68 offset:336
	ds_read_b128 v[168:171], v69 offset:672
	ds_read_b128 v[172:175], v69 offset:688
	ds_read_b128 v[150:153], v68 offset:352
	ds_read_b128 v[176:179], v69 offset:704
	ds_read_b128 v[180:183], v69 offset:720
	ds_read_b128 v[154:157], v68 offset:368
	ds_read_b128 v[184:187], v69 offset:736
	ds_read_b128 v[188:191], v69 offset:752
	s_waitcnt lgkmcnt(15)
	v_lshlrev_b32_e32 v126, 16, v70
	v_and_b32_e32 v127, s7, v70
	v_pk_fma_f32 v[86:87], v[94:95], v[126:127], v[86:87]
	v_lshlrev_b32_e32 v128, 16, v71
	v_and_b32_e32 v129, s7, v71
	v_pk_fma_f32 v[192:193], v[96:97], v[128:129], v[192:193]
	v_lshlrev_b32_e32 v130, 16, v72
	v_and_b32_e32 v131, s7, v72
	v_pk_fma_f32 v[194:195], v[98:99], v[130:131], v[194:195]
	v_lshlrev_b32_e32 v132, 16, v73
	v_and_b32_e32 v133, s7, v73
	v_pk_fma_f32 v[204:205], v[100:101], v[132:133], v[204:205]
	s_waitcnt lgkmcnt(15)
	v_lshlrev_b32_e32 v134, 16, v74
	v_and_b32_e32 v135, s7, v74
	v_pk_fma_f32 v[86:87], v[102:103], v[134:135], v[86:87]
	v_lshlrev_b32_e32 v136, 16, v75
	v_and_b32_e32 v137, s7, v75
	v_pk_fma_f32 v[192:193], v[104:105], v[136:137], v[192:193]
	v_lshlrev_b32_e32 v138, 16, v76
	v_and_b32_e32 v139, s7, v76
	v_pk_fma_f32 v[194:195], v[106:107], v[138:139], v[194:195]
	v_lshlrev_b32_e32 v140, 16, v77
	v_and_b32_e32 v141, s7, v77
	v_pk_fma_f32 v[204:205], v[108:109], v[140:141], v[204:205]
	s_waitcnt lgkmcnt(15)
	v_lshlrev_b32_e32 v126, 16, v78
	v_and_b32_e32 v127, s7, v78
	v_pk_fma_f32 v[86:87], v[110:111], v[126:127], v[86:87]
	v_lshlrev_b32_e32 v128, 16, v79
	v_and_b32_e32 v129, s7, v79
	v_pk_fma_f32 v[192:193], v[112:113], v[128:129], v[192:193]
	v_lshlrev_b32_e32 v130, 16, v80
	v_and_b32_e32 v131, s7, v80
	v_pk_fma_f32 v[194:195], v[114:115], v[130:131], v[194:195]
	v_lshlrev_b32_e32 v132, 16, v81
	v_and_b32_e32 v133, s7, v81
	v_pk_fma_f32 v[204:205], v[116:117], v[132:133], v[204:205]
	s_waitcnt lgkmcnt(12)
	v_lshlrev_b32_e32 v134, 16, v82
	v_and_b32_e32 v135, s7, v82
	v_pk_fma_f32 v[86:87], v[118:119], v[134:135], v[86:87]
	v_lshlrev_b32_e32 v136, 16, v83
	v_and_b32_e32 v137, s7, v83
	v_pk_fma_f32 v[192:193], v[120:121], v[136:137], v[192:193]
	v_lshlrev_b32_e32 v138, 16, v84
	v_and_b32_e32 v139, s7, v84
	v_pk_fma_f32 v[194:195], v[122:123], v[138:139], v[194:195]
	v_lshlrev_b32_e32 v140, 16, v85
	v_and_b32_e32 v141, s7, v85
	v_pk_fma_f32 v[204:205], v[124:125], v[140:141], v[204:205]
	ds_read_b128 v[70:73], v68 offset:384
	ds_read_b128 v[94:97], v69 offset:768
	ds_read_b128 v[98:101], v69 offset:784
	ds_read_b128 v[74:77], v68 offset:400
	ds_read_b128 v[102:105], v69 offset:800
	ds_read_b128 v[106:109], v69 offset:816
	ds_read_b128 v[78:81], v68 offset:416
	ds_read_b128 v[110:113], v69 offset:832
	ds_read_b128 v[114:117], v69 offset:848
	ds_read_b128 v[82:85], v68 offset:432
	ds_read_b128 v[118:121], v69 offset:864
	ds_read_b128 v[122:125], v69 offset:880
	s_waitcnt lgkmcnt(15)
	v_lshlrev_b32_e32 v126, 16, v142
	v_and_b32_e32 v127, s7, v142
	v_pk_fma_f32 v[86:87], v[160:161], v[126:127], v[86:87]
	v_lshlrev_b32_e32 v128, 16, v143
	v_and_b32_e32 v129, s7, v143
	v_pk_fma_f32 v[192:193], v[162:163], v[128:129], v[192:193]
	v_lshlrev_b32_e32 v130, 16, v144
	v_and_b32_e32 v131, s7, v144
	v_pk_fma_f32 v[194:195], v[164:165], v[130:131], v[194:195]
	v_lshlrev_b32_e32 v132, 16, v145
	v_and_b32_e32 v133, s7, v145
	v_pk_fma_f32 v[204:205], v[166:167], v[132:133], v[204:205]
	s_waitcnt lgkmcnt(15)
	v_lshlrev_b32_e32 v134, 16, v146
	v_and_b32_e32 v135, s7, v146
	v_pk_fma_f32 v[86:87], v[168:169], v[134:135], v[86:87]
	v_lshlrev_b32_e32 v136, 16, v147
	v_and_b32_e32 v137, s7, v147
	v_pk_fma_f32 v[192:193], v[170:171], v[136:137], v[192:193]
	v_lshlrev_b32_e32 v138, 16, v148
	v_and_b32_e32 v139, s7, v148
	v_pk_fma_f32 v[194:195], v[172:173], v[138:139], v[194:195]
	v_lshlrev_b32_e32 v140, 16, v149
	v_and_b32_e32 v141, s7, v149
	v_pk_fma_f32 v[204:205], v[174:175], v[140:141], v[204:205]
	s_waitcnt lgkmcnt(15)
; #define LAS __attribute__((address_space(3)))
; __device__ __forceinline__ float bf_lo(unsigned w) { return __uint_as_float(w << 16); }
; __device__ __forceinline__ float bf_hi(unsigned w) { return __uint_as_float(w & 0xffff0000u); }
; __device__ void passB_unit(const Params& p, LAS unsigned char* lds, int u, bool do_store = true) {
;     ...
;         for (int k8 = 0; k8 < 32; ++k8) { const u32x4 qv = *(const LAS u32x4*)(Qs + t * 264 + k8 * 8); const LAS float* np = nv + k8 * 8;
;             s += bf_lo(qv.x) * np[0] + bf_hi(qv.x) * np[1] + bf_lo(qv.y) * np[2] + bf_hi(qv.y) * np[3] + bf_lo(qv.z) * np[4] + bf_hi(qv.z) * np[5] + bf_lo(qv.w) * np[6] + bf_hi(qv.w) * np[7]; }
;         nqA[dt] = s; }
	v_lshlrev_b32_e32 v126, 16, v150
	v_and_b32_e32 v127, s7, v150
	v_pk_fma_f32 v[86:87], v[176:177], v[126:127], v[86:87]
	v_lshlrev_b32_e32 v128, 16, v151
	v_and_b32_e32 v129, s7, v151
	v_pk_fma_f32 v[192:193], v[178:179], v[128:129], v[192:193]
	v_lshlrev_b32_e32 v130, 16, v152
	v_and_b32_e32 v131, s7, v152
	v_pk_fma_f32 v[194:195], v[180:181], v[130:131], v[194:195]
	v_lshlrev_b32_e32 v132, 16, v153
	v_and_b32_e32 v133, s7, v153
	v_pk_fma_f32 v[204:205], v[182:183], v[132:133], v[204:205]
	s_waitcnt lgkmcnt(12)
	v_lshlrev_b32_e32 v134, 16, v154
	v_and_b32_e32 v135, s7, v154
	v_pk_fma_f32 v[86:87], v[184:185], v[134:135], v[86:87]
	v_lshlrev_b32_e32 v136, 16, v155
	v_and_b32_e32 v137, s7, v155
	v_pk_fma_f32 v[192:193], v[186:187], v[136:137], v[192:193]
	v_lshlrev_b32_e32 v138, 16, v156
	v_and_b32_e32 v139, s7, v156
	v_pk_fma_f32 v[194:195], v[188:189], v[138:139], v[194:195]
	v_lshlrev_b32_e32 v140, 16, v157
	v_and_b32_e32 v141, s7, v157
	v_pk_fma_f32 v[204:205], v[190:191], v[140:141], v[204:205]
	ds_read_b128 v[142:145], v68 offset:448
	ds_read_b128 v[160:163], v69 offset:896
	ds_read_b128 v[164:167], v69 offset:912
	ds_read_b128 v[146:149], v68 offset:464
	ds_read_b128 v[168:171], v69 offset:928
	ds_read_b128 v[172:175], v69 offset:944
	ds_read_b128 v[150:153], v68 offset:480
	ds_read_b128 v[176:179], v69 offset:960
	ds_read_b128 v[180:183], v69 offset:976
	ds_read_b128 v[154:157], v68 offset:496
	ds_read_b128 v[184:187], v69 offset:992
	ds_read_b128 v[188:191], v69 offset:1008
	s_waitcnt lgkmcnt(15)
	v_lshlrev_b32_e32 v126, 16, v70
	v_and_b32_e32 v127, s7, v70
	v_pk_fma_f32 v[86:87], v[94:95], v[126:127], v[86:87]
	v_lshlrev_b32_e32 v128, 16, v71
	v_and_b32_e32 v129, s7, v71
	v_pk_fma_f32 v[192:193], v[96:97], v[128:129], v[192:193]
	v_lshlrev_b32_e32 v130, 16, v72
	v_and_b32_e32 v131, s7, v72
	v_pk_fma_f32 v[194:195], v[98:99], v[130:131], v[194:195]
	v_lshlrev_b32_e32 v132, 16, v73
	v_and_b32_e32 v133, s7, v73
	v_pk_fma_f32 v[204:205], v[100:101], v[132:133], v[204:205]
	s_waitcnt lgkmcnt(15)
	v_lshlrev_b32_e32 v134, 16, v74
	v_and_b32_e32 v135, s7, v74
	v_pk_fma_f32 v[86:87], v[102:103], v[134:135], v[86:87]
	v_lshlrev_b32_e32 v136, 16, v75
	v_and_b32_e32 v137, s7, v75
	v_pk_fma_f32 v[192:193], v[104:105], v[136:137], v[192:193]
	v_lshlrev_b32_e32 v138, 16, v76
	v_and_b32_e32 v139, s7, v76
	v_pk_fma_f32 v[194:195], v[106:107], v[138:139], v[194:195]
	v_lshlrev_b32_e32 v140, 16, v77
	v_and_b32_e32 v141, s7, v77
	v_pk_fma_f32 v[204:205], v[108:109], v[140:141], v[204:205]
	s_waitcnt lgkmcnt(15)
	v_lshlrev_b32_e32 v126, 16, v78
	v_and_b32_e32 v127, s7, v78
	v_pk_fma_f32 v[86:87], v[110:111], v[126:127], v[86:87]
	v_lshlrev_b32_e32 v128, 16, v79
	v_and_b32_e32 v129, s7, v79
	v_pk_fma_f32 v[192:193], v[112:113], v[128:129], v[192:193]
	v_lshlrev_b32_e32 v130, 16, v80
	v_and_b32_e32 v131, s7, v80
	v_pk_fma_f32 v[194:195], v[114:115], v[130:131], v[194:195]
	v_lshlrev_b32_e32 v132, 16, v81
	v_and_b32_e32 v133, s7, v81
	v_pk_fma_f32 v[204:205], v[116:117], v[132:133], v[204:205]
	s_waitcnt lgkmcnt(12)
	v_lshlrev_b32_e32 v134, 16, v82
	v_and_b32_e32 v135, s7, v82
	v_pk_fma_f32 v[86:87], v[118:119], v[134:135], v[86:87]
	v_lshlrev_b32_e32 v136, 16, v83
	v_and_b32_e32 v137, s7, v83
	v_pk_fma_f32 v[192:193], v[120:121], v[136:137], v[192:193]
	v_lshlrev_b32_e32 v138, 16, v84
	v_and_b32_e32 v139, s7, v84
	v_pk_fma_f32 v[194:195], v[122:123], v[138:139], v[194:195]
	v_lshlrev_b32_e32 v140, 16, v85
	v_and_b32_e32 v141, s7, v85
	v_pk_fma_f32 v[204:205], v[124:125], v[140:141], v[204:205]
	s_waitcnt lgkmcnt(9)
	v_lshlrev_b32_e32 v126, 16, v142
	v_and_b32_e32 v127, s7, v142
	v_pk_fma_f32 v[86:87], v[160:161], v[126:127], v[86:87]
	v_lshlrev_b32_e32 v128, 16, v143
	v_and_b32_e32 v129, s7, v143
	v_pk_fma_f32 v[192:193], v[162:163], v[128:129], v[192:193]
	v_lshlrev_b32_e32 v130, 16, v144
	v_and_b32_e32 v131, s7, v144
	v_pk_fma_f32 v[194:195], v[164:165], v[130:131], v[194:195]
	v_lshlrev_b32_e32 v132, 16, v145
	v_and_b32_e32 v133, s7, v145
	v_pk_fma_f32 v[204:205], v[166:167], v[132:133], v[204:205]
	s_waitcnt lgkmcnt(6)
	v_lshlrev_b32_e32 v134, 16, v146
	v_and_b32_e32 v135, s7, v146
	v_pk_fma_f32 v[86:87], v[168:169], v[134:135], v[86:87]
	v_lshlrev_b32_e32 v136, 16, v147
	v_and_b32_e32 v137, s7, v147
	v_pk_fma_f32 v[192:193], v[170:171], v[136:137], v[192:193]
	v_lshlrev_b32_e32 v138, 16, v148
	v_and_b32_e32 v139, s7, v148
	v_pk_fma_f32 v[194:195], v[172:173], v[138:139], v[194:195]
	v_lshlrev_b32_e32 v140, 16, v149
	v_and_b32_e32 v141, s7, v149
	v_pk_fma_f32 v[204:205], v[174:175], v[140:141], v[204:205]
	s_waitcnt lgkmcnt(3)
	v_lshlrev_b32_e32 v126, 16, v150
	v_and_b32_e32 v127, s7, v150
	v_pk_fma_f32 v[86:87], v[176:177], v[126:127], v[86:87]
	v_lshlrev_b32_e32 v128, 16, v151
	v_and_b32_e32 v129, s7, v151
	v_pk_fma_f32 v[192:193], v[178:179], v[128:129], v[192:193]
	v_lshlrev_b32_e32 v130, 16, v152
	v_and_b32_e32 v131, s7, v152
	v_pk_fma_f32 v[194:195], v[180:181], v[130:131], v[194:195]
	v_lshlrev_b32_e32 v132, 16, v153
	v_and_b32_e32 v133, s7, v153
	v_pk_fma_f32 v[204:205], v[182:183], v[132:133], v[204:205]
	s_waitcnt lgkmcnt(0)
	v_lshlrev_b32_e32 v134, 16, v154
	v_and_b32_e32 v135, s7, v154
	v_pk_fma_f32 v[86:87], v[184:185], v[134:135], v[86:87]
	v_lshlrev_b32_e32 v136, 16, v155
	v_and_b32_e32 v137, s7, v155
	v_pk_fma_f32 v[192:193], v[186:187], v[136:137], v[192:193]
	v_lshlrev_b32_e32 v138, 16, v156
	v_and_b32_e32 v139, s7, v156
	v_pk_fma_f32 v[194:195], v[188:189], v[138:139], v[194:195]
	v_lshlrev_b32_e32 v140, 16, v157
	v_and_b32_e32 v141, s7, v157
	v_pk_fma_f32 v[204:205], v[190:191], v[140:141], v[204:205]
	v_pk_add_f32 v[86:87], v[86:87], v[192:193]
	v_pk_add_f32 v[194:195], v[194:195], v[204:205]
	v_pk_add_f32 v[86:87], v[86:87], v[194:195]
	v_add_f32_e32 v60, v86, v87
	v_add_u32_e32 v61, 0x23000, v63
	ds_write_b32 v61, v60

; #define PG8_STAGE(bufoff, gbase, voff) do { _Pragma("unroll") for (int _i = 0; _i < 2; ++_i) \
;         __builtin_amdgcn_global_load_lds((const unsigned*)((const char*)(gbase) + (voff)[_i]), (LAS unsigned*)(lds + (bufoff) + ldsw + _i * 8192), 16, 0, 0); } while (0)
; #define PG8_WAIT_V(n) asm volatile("s_waitcnt vmcnt(" #n ")" ::: "memory")
; #define PG8_BAR __builtin_amdgcn_s_barrier()
; template <class Epi, class Sched, bool ZERO>
; __device__ __forceinline__ void gemm_phase_acc(LAS unsigned char* lds, const Gemm g, const Sched& S, const Epi& E, f32x4 (&acc)[2][2][4][2]) {
;     ...
;     if constexpr (ZERO) {
; #pragma unroll
;     for (int a = 0; a < 2; ++a)
; #pragma unroll
;         for (int b = 0; b < 2; ++b)
; #pragma unroll
;             for (int m = 0; m < 4; ++m)
; #pragma unroll
;                 for (int n = 0; n < 2; ++n) acc[a][b][m][n] = (f32x4){0.f, 0.f, 0.f, 0.f};
;     }
;     bf16x8 At[4][2], B0[2][2], B1[2][2];
;     const char* cA = (const char*)g.A + (size_t)cur.pm * tstep; const char* cB = (const char*)g.Bt + (size_t)cur.pn * tstep;
;     PG8_STAGE(PG8_SB(0, 0), cB, voffB); PG8_STAGE(PG8_SA(0, 0), cA, voffA); PG8_STAGE(PG8_SB(0, 1), cB + hstep, voffB); PG8_STAGE(PG8_SA(0, 1), cA + hstep, voffA);
;     if (wr == 1) PG8_BAR;
;     PG8_WAIT_V(4); PG8_BAR;
;     PG8_STAGE(PG8_SB(1, 0), cB + kstep, voffB); PG8_STAGE(PG8_SA(1, 0), cA + kstep, voffA); PG8_STAGE(PG8_SB(1, 1), cB + hstep + kstep, voffB);
;     PG8_WAIT_V(6); PG8_BAR;
.LBB0_630:
	v_and_b32_e32 v15, 15, v13
	v_bfe_u32 v16, v13, 4, 2
	s_and_b32 s17, s3, 3
	v_lshl_or_b32 v85, s4, 6, v15
	v_lshlrev_b32_e32 v84, 4, v16
	s_lshl_b32 s3, s4, 13
	v_lshlrev_b32_e32 v13, 2, v13
	s_mov_b64 s[4:5], 0x80
	v_lshl_or_b32 v15, v15, 6, v84
	v_and_b32_e32 v13, 32, v13
	s_add_i32 m0, s11, 0x18000
	v_lshl_add_u64 v[6:7], v[6:7], 0, s[4:5]
	v_bitop3_b32 v16, v15, s3, v13 bitop3:0xde
	s_lshl_b32 s3, s17, 12
	s_waitcnt vmcnt(4)
	s_barrier
	global_load_lds_dwordx4 v[6:7], off
	v_lshl_add_u64 v[4:5], v[4:5], 0, s[4:5]
	s_add_i32 m0, s11, 0x1a000
	s_add_i32 s24, s11, 0x8000
	s_add_i32 s25, s11, 0xa000
	global_load_lds_dwordx4 v[4:5], off
	v_lshl_add_u64 v[2:3], v[2:3], 0, s[4:5]
	s_mov_b32 m0, s24
	s_add_u32 s26, s0, 0x40080
	global_load_lds_dwordx4 v[2:3], off
	v_lshl_add_u64 v[0:1], v[0:1], 0, s[4:5]
	s_mov_b32 m0, s25
	s_addc_u32 s27, s1, 0
	global_load_lds_dwordx4 v[0:1], off
	s_add_i32 m0, s11, 0x1c000
	v_lshl_add_u64 v[0:1], s[26:27], 0, v[50:51]
	global_load_lds_dwordx4 v[0:1], off
	v_lshl_add_u64 v[0:1], s[26:27], 0, v[62:63]
	s_add_i32 m0, s11, 0x1e000
	v_readlane_b32 s26, v254, 26
	global_load_lds_dwordx4 v[0:1], off
	v_lshlrev_b32_e32 v0, 14, v8
	v_and_b32_e32 v0, 0xffff8000, v0
	v_lshl_add_u32 v0, v9, 11, v0
	v_and_b32_e32 v1, 1, v8
	v_lshl_or_b32 v0, v1, 6, v0
	v_readlane_b32 s27, v254, 27
	s_add_u32 s26, s70, s26
	v_lshl_add_u32 v0, v10, 1, v0
	v_mov_b32_e32 v1, v51
	s_addc_u32 s27, s71, s27
	s_mov_b64 s[8:9], 0x40080
	v_lshl_add_u64 v[0:1], s[26:27], 0, v[0:1]
	v_lshl_add_u64 v[72:73], v[0:1], 0, s[8:9]
	v_lshlrev_b32_e32 v0, 14, v11
	v_and_b32_e32 v0, 0xffff8000, v0
	s_lshl_b32 s2, s2, 16
	v_lshl_add_u32 v0, v12, 11, v0
	v_and_b32_e32 v1, 1, v11
	s_and_b32 s2, s2, 0x180000
	v_lshl_or_b32 v0, v1, 6, v0
	s_add_u32 s2, s70, s2
	v_bitop3_b32 v13, v15, s3, v13 bitop3:0xde
	v_lshl_add_u32 v0, v14, 1, v0
	v_mov_b32_e32 v1, v51
	s_addc_u32 s3, s71, 0
	s_waitcnt vmcnt(6)
	v_lshl_add_u64 v[0:1], s[26:27], 0, v[0:1]
	s_add_u32 s26, s2, 0x2e00100
	s_addc_u32 s27, s3, 0
	s_add_i32 s31, s35, s6
	s_add_i32 s39, s22, s6
	s_add_i32 s41, s23, s6
	s_add_i32 s43, s33, s6
	v_lshl_add_u64 v[74:75], v[0:1], 0, s[8:9]
	s_mov_b32 s28, -2
	s_mov_b64 s[2:3], 0
	v_add_u32_e32 v86, s35, v13
	v_add_u32_e32 v87, 0, v16
	s_add_i32 s29, s11, 0xc000
	s_add_i32 s30, s11, 0xe000
	v_add_u32_e32 v88, s22, v13
	s_add_i32 s38, s31, 0x2000
	s_add_i32 s40, s39, 0x2000
	v_add_u32_e32 v89, s23, v13
	v_add_u32_e32 v90, s33, v13
	s_add_i32 s42, s41, 0x2000
	s_add_i32 s44, s43, 0x2000
	v_mov_b32_e32 v0, v51
	v_mov_b32_e32 v1, v51
	v_mov_b32_e32 v2, v51
	v_mov_b32_e32 v3, v51
	v_mov_b32_e32 v4, v51
	v_mov_b32_e32 v5, v51
	v_mov_b32_e32 v6, v51
	v_mov_b32_e32 v7, v51
	v_mov_b32_e32 v16, v51
	v_mov_b32_e32 v17, v51
	v_mov_b32_e32 v18, v51
	v_mov_b32_e32 v19, v51
	v_mov_b32_e32 v20, v51
	v_mov_b32_e32 v21, v51
	v_mov_b32_e32 v22, v51
	v_mov_b32_e32 v23, v51
	v_mov_b32_e32 v32, v51
	v_mov_b32_e32 v33, v51
	v_mov_b32_e32 v34, v51
	v_mov_b32_e32 v35, v51
	v_mov_b32_e32 v36, v51
	v_mov_b32_e32 v37, v51
	v_mov_b32_e32 v38, v51
	v_mov_b32_e32 v39, v51
	v_mov_b32_e32 v52, v51
	v_mov_b32_e32 v53, v51
	v_mov_b32_e32 v54, v51
	v_mov_b32_e32 v55, v51
	v_mov_b32_e32 v56, v51
	v_mov_b32_e32 v57, v51
	v_mov_b32_e32 v58, v51
	v_mov_b32_e32 v59, v51
	v_mov_b32_e32 v8, v51
	v_mov_b32_e32 v9, v51
	v_mov_b32_e32 v10, v51
	v_mov_b32_e32 v11, v51
	v_mov_b32_e32 v12, v51
	v_mov_b32_e32 v13, v51
	v_mov_b32_e32 v14, v51
	v_mov_b32_e32 v15, v51
	v_mov_b32_e32 v24, v51
	v_mov_b32_e32 v25, v51
	v_mov_b32_e32 v26, v51
	v_mov_b32_e32 v27, v51
	v_mov_b32_e32 v28, v51
	v_mov_b32_e32 v29, v51
	v_mov_b32_e32 v30, v51
	v_mov_b32_e32 v31, v51
	v_mov_b32_e32 v40, v51
	v_mov_b32_e32 v41, v51
	v_mov_b32_e32 v42, v51
	v_mov_b32_e32 v43, v51
	v_mov_b32_e32 v44, v51
	v_mov_b32_e32 v45, v51
	v_mov_b32_e32 v46, v51
	v_mov_b32_e32 v47, v51
	v_mov_b32_e32 v64, v51
	v_mov_b32_e32 v65, v51
	v_mov_b32_e32 v66, v51
	v_mov_b32_e32 v67, v51
	v_mov_b32_e32 v68, v51
	v_mov_b32_e32 v69, v51
	v_mov_b32_e32 v70, v51
	v_mov_b32_e32 v71, v51
	v_mov_b32_e32 v76, v51
	v_mov_b32_e32 v77, v51
	v_mov_b32_e32 v78, v51
	v_mov_b32_e32 v79, v51
	v_mov_b32_e32 v80, v51
	v_mov_b32_e32 v81, v51
	v_mov_b32_e32 v82, v51
	v_mov_b32_e32 v83, v51
	v_mov_b32_e32 v104, v51
	v_mov_b32_e32 v105, v51
	v_mov_b32_e32 v106, v51
	v_mov_b32_e32 v107, v51
	v_mov_b32_e32 v108, v51
	v_mov_b32_e32 v109, v51
	v_mov_b32_e32 v110, v51
	v_mov_b32_e32 v111, v51
	v_mov_b32_e32 v128, v51
	v_mov_b32_e32 v129, v51
	v_mov_b32_e32 v130, v51
	v_mov_b32_e32 v131, v51
	v_mov_b32_e32 v132, v51
	v_mov_b32_e32 v133, v51
	v_mov_b32_e32 v134, v51
	v_mov_b32_e32 v135, v51
	v_mov_b32_e32 v144, v51
	v_mov_b32_e32 v145, v51
	v_mov_b32_e32 v146, v51
	v_mov_b32_e32 v147, v51
	v_mov_b32_e32 v148, v51
	v_mov_b32_e32 v149, v51
	v_mov_b32_e32 v150, v51
	v_mov_b32_e32 v151, v51
	v_mov_b32_e32 v92, v51
	v_mov_b32_e32 v93, v51
	v_mov_b32_e32 v94, v51
	v_mov_b32_e32 v95, v51
	v_mov_b32_e32 v96, v51
	v_mov_b32_e32 v97, v51
	v_mov_b32_e32 v98, v51
	v_mov_b32_e32 v99, v51
	v_mov_b32_e32 v116, v51
	v_mov_b32_e32 v117, v51
	v_mov_b32_e32 v118, v51
	v_mov_b32_e32 v119, v51
	v_mov_b32_e32 v120, v51
	v_mov_b32_e32 v121, v51
	v_mov_b32_e32 v122, v51
	v_mov_b32_e32 v123, v51
	v_mov_b32_e32 v136, v51
	v_mov_b32_e32 v137, v51
	v_mov_b32_e32 v138, v51
	v_mov_b32_e32 v139, v51
	v_mov_b32_e32 v140, v51
	v_mov_b32_e32 v141, v51
	v_mov_b32_e32 v142, v51
	v_mov_b32_e32 v143, v51
	v_mov_b32_e32 v152, v51
	v_mov_b32_e32 v153, v51
	v_mov_b32_e32 v154, v51
	v_mov_b32_e32 v155, v51
	v_mov_b32_e32 v156, v51
	v_mov_b32_e32 v157, v51
	v_mov_b32_e32 v158, v51
	v_mov_b32_e32 v159, v51
	s_barrier
	s_nop 0
	s_nop 0
	s_nop 0
	s_nop 0
